# v26 + FoX/stick-breaking epilogues: the four gate-row loads issued up front into dead registers (counted waits) instead of four dependent round trips
# speedup vs baseline: 1.0125x; 1.0015x over previous
.LBB0_288:
	s_or_b64 exec, exec, s[4:5]
	v_add_u32_e32 v40, s75, v108
	ds_read_b128 v[32:35], v40 offset:58112
	ds_read_b128 v[36:39], v40 offset:58144
	s_ashr_i32 s17, s54, 31
	s_add_u32 s4, s19, s54
	s_addc_u32 s5, s52, s17
	s_waitcnt lgkmcnt(1)
	v_mul_f32_e32 v41, v0, v32
	v_mul_f32_e32 v16, v16, v32
	v_mul_f32_e32 v32, v1, v33
	v_mul_f32_e32 v17, v17, v33
	v_mul_f32_e32 v33, v2, v34
	v_mul_f32_e32 v18, v18, v34
	v_mul_f32_e32 v34, v3, v35
	ds_read_b128 v[0:3], v40 offset:58176
	s_lshl_b64 s[4:5], s[4:5], 7
	v_mul_f32_e32 v19, v19, v35
	s_waitcnt lgkmcnt(1)
	v_mul_f32_e32 v4, v4, v36
	v_mul_f32_e32 v20, v20, v36
	s_waitcnt lgkmcnt(0)
	v_mul_f32_e32 v8, v8, v0
	v_mul_f32_e32 v24, v24, v0
	v_mul_f32_e32 v9, v9, v1
	v_mul_f32_e32 v25, v25, v1
	v_mul_f32_e32 v10, v10, v2
	v_mul_f32_e32 v26, v26, v2
	v_mul_f32_e32 v11, v11, v3
	v_mul_f32_e32 v27, v27, v3
	ds_read_b128 v[0:3], v40 offset:58208
	v_mul_f32_e32 v5, v5, v37
	v_mul_f32_e32 v21, v21, v37
	v_mul_f32_e32 v6, v6, v38
	v_mul_f32_e32 v22, v22, v38
	v_mul_f32_e32 v7, v7, v39
	v_mul_f32_e32 v23, v23, v39
	s_waitcnt lgkmcnt(0)
	v_mul_f32_e32 v12, v12, v0
	v_mul_f32_e32 v0, v28, v0
	v_mul_f32_e32 v13, v13, v1
	v_mul_f32_e32 v1, v29, v1
	v_mul_f32_e32 v14, v14, v2
	v_mul_f32_e32 v2, v30, v2
	v_mul_f32_e32 v15, v15, v3
	v_mul_f32_e32 v3, v31, v3
	ds_write_b32 v150, v41 offset:60416
	ds_write_b32 v151, v16 offset:60416
	ds_write_b32 v150, v32 offset:60672
	ds_write_b32 v152, v17 offset:60416
	ds_write_b32 v150, v33 offset:60928
	ds_write_b32 v153, v18 offset:60416
	ds_write_b32 v150, v34 offset:61184
	ds_write_b32 v154, v19 offset:60416
	ds_write_b32 v150, v4 offset:62464
	ds_write_b32 v155, v20 offset:60416
	ds_write_b32 v150, v5 offset:62720
	ds_write_b32 v156, v21 offset:60416
	ds_write_b32 v150, v6 offset:62976
	ds_write_b32 v157, v22 offset:60416
	ds_write_b32 v150, v7 offset:63232
	ds_write_b32 v158, v23 offset:60416
	ds_write_b32 v150, v8 offset:64512
	ds_write_b32 v159, v24 offset:60416
	ds_write_b32 v150, v9 offset:64768
	ds_write_b32 v164, v25 offset:60416
	ds_write_b32 v150, v10 offset:65024
	ds_write_b32 v165, v26 offset:60416
	ds_write_b32 v150, v11 offset:65280
	ds_write_b32 v166, v27 offset:60416
	ds_write_b32 v167, v12
	ds_write_b32 v168, v0 offset:60416
	ds_write_b32 v169, v13
	ds_write_b32 v170, v1 offset:60416
	ds_write_b32 v171, v14
	ds_write_b32 v172, v2 offset:60416
	ds_write_b32 v173, v15
	ds_write_b32 v174, v3 offset:60416
	v_lshl_add_u64 v[10:11], v[112:113], 0, s[4:5]
	v_lshl_add_u64 v[12:13], v[10:11], 0, v[160:161]
	v_lshl_add_u64 v[64:65], v[10:11], 0, v[118:119]
	v_lshl_add_u64 v[68:69], v[10:11], 0, v[122:123]
	v_lshl_add_u64 v[72:73], v[10:11], 0, v[126:127]
	ds_read_b128 v[0:3], v185 offset:60416
	ds_read_b128 v[4:7], v185 offset:60432
	global_load_dwordx4 v[12:15], v[12:13], off
	global_load_dwordx4 v[64:67], v[64:65], off
	global_load_dwordx4 v[68:71], v[68:69], off
	global_load_dwordx4 v[72:75], v[72:73], off
	s_add_u32 s16, s88, s54
	s_addc_u32 s17, s89, s17
	s_lshl_b64 s[48:49], s[16:17], 12
	v_lshl_add_u64 v[8:9], v[134:135], 0, s[48:49]
	s_add_i32 s53, s53, 1
	s_cmp_eq_u32 s53, 4
	s_waitcnt vmcnt(3)
	v_lshlrev_b32_e32 v16, 16, v12
	v_and_b32_e32 v17, 0xffff0000, v12
	v_mul_f32_e32 v12, 0xbfb8aa3b, v16
	v_exp_f32_e32 v12, v12
	s_waitcnt lgkmcnt(1)
	v_pk_mul_f32 v[0:1], v[0:1], v[16:17]
	v_add_f32_e32 v12, 1.0, v12
	v_rcp_f32_e32 v18, v12
	v_mul_f32_e32 v12, 0xbfb8aa3b, v17
	v_exp_f32_e32 v12, v12
	s_nop 0
	v_add_f32_e32 v12, 1.0, v12
	v_rcp_f32_e32 v19, v12
	v_lshlrev_b32_e32 v12, 16, v13
	v_and_b32_e32 v13, 0xffff0000, v13
	v_mul_f32_e32 v16, 0xbfb8aa3b, v12
	v_pk_mul_f32 v[2:3], v[2:3], v[12:13]
	v_mul_f32_e32 v12, 0xbfb8aa3b, v13
	v_exp_f32_e32 v12, v12
	v_exp_f32_e32 v16, v16
	v_and_b32_e32 v13, 0xffff0000, v14
	v_pk_mul_f32 v[0:1], v[0:1], v[18:19]
	v_add_f32_e32 v12, 1.0, v12
	v_rcp_f32_e32 v17, v12
	v_lshlrev_b32_e32 v12, 16, v14
	v_mul_f32_e32 v14, 0xbfb8aa3b, v12
	s_waitcnt lgkmcnt(0)
	v_pk_mul_f32 v[4:5], v[4:5], v[12:13]
	v_mul_f32_e32 v12, 0xbfb8aa3b, v13
	v_add_f32_e32 v16, 1.0, v16
	v_exp_f32_e32 v12, v12
	v_rcp_f32_e32 v16, v16
	v_exp_f32_e32 v14, v14
	v_and_b32_e32 v13, 0xffff0000, v15
	v_add_f32_e32 v12, 1.0, v12
	v_pk_mul_f32 v[2:3], v[2:3], v[16:17]
	v_add_f32_e32 v14, 1.0, v14
	v_rcp_f32_e32 v17, v12
	v_lshlrev_b32_e32 v12, 16, v15
	v_rcp_f32_e32 v16, v14
	v_mul_f32_e32 v14, 0xbfb8aa3b, v12
	v_pk_mul_f32 v[6:7], v[6:7], v[12:13]
	v_mul_f32_e32 v12, 0xbfb8aa3b, v13
	v_exp_f32_e32 v14, v14
	v_exp_f32_e32 v12, v12
	v_pk_mul_f32 v[4:5], v[4:5], v[16:17]
	v_cvt_pk_bf16_f32 v0, v0, v1
	v_add_f32_e32 v14, 1.0, v14
	v_add_f32_e32 v12, 1.0, v12
	v_rcp_f32_e32 v14, v14
	v_rcp_f32_e32 v15, v12
	v_cvt_pk_bf16_f32 v1, v2, v3
	v_cvt_pk_bf16_f32 v2, v4, v5
	v_lshl_add_u64 v[4:5], v[8:9], 0, v[116:117]
	v_pk_mul_f32 v[6:7], v[6:7], v[14:15]
	v_lshl_add_u64 v[12:13], v[10:11], 0, v[118:119]
	v_cvt_pk_bf16_f32 v3, v6, v7
	global_store_dwordx4 v[4:5], v[0:3], off
	ds_read_b128 v[4:7], v186 offset:60416
	ds_read_b128 v[0:3], v186 offset:60432
	s_waitcnt vmcnt(3)
	v_mov_b32_e32 v12, v64
	v_mov_b32_e32 v13, v65
	v_mov_b32_e32 v14, v66
	v_mov_b32_e32 v15, v67
	v_lshlrev_b32_e32 v16, 16, v12
	v_and_b32_e32 v17, 0xffff0000, v12
	v_mul_f32_e32 v12, 0xbfb8aa3b, v16
	v_exp_f32_e32 v12, v12
	s_waitcnt lgkmcnt(1)
	v_pk_mul_f32 v[4:5], v[4:5], v[16:17]
	v_add_f32_e32 v12, 1.0, v12
	v_rcp_f32_e32 v18, v12
	v_mul_f32_e32 v12, 0xbfb8aa3b, v17
	v_exp_f32_e32 v12, v12
	s_nop 0
	v_add_f32_e32 v12, 1.0, v12
	v_rcp_f32_e32 v19, v12
	v_lshlrev_b32_e32 v12, 16, v13
	v_and_b32_e32 v13, 0xffff0000, v13
	v_mul_f32_e32 v16, 0xbfb8aa3b, v12
	v_pk_mul_f32 v[6:7], v[6:7], v[12:13]
	v_mul_f32_e32 v12, 0xbfb8aa3b, v13
	v_exp_f32_e32 v12, v12
	v_exp_f32_e32 v16, v16
	v_and_b32_e32 v13, 0xffff0000, v14
	v_pk_mul_f32 v[4:5], v[4:5], v[18:19]
	v_add_f32_e32 v12, 1.0, v12
	v_rcp_f32_e32 v17, v12
	v_lshlrev_b32_e32 v12, 16, v14
	v_mul_f32_e32 v14, 0xbfb8aa3b, v12
	s_waitcnt lgkmcnt(0)
	v_pk_mul_f32 v[0:1], v[0:1], v[12:13]
	v_mul_f32_e32 v12, 0xbfb8aa3b, v13
	v_add_f32_e32 v16, 1.0, v16
	v_exp_f32_e32 v14, v14
	v_exp_f32_e32 v12, v12
	v_rcp_f32_e32 v16, v16
	v_add_f32_e32 v14, 1.0, v14
	v_add_f32_e32 v12, 1.0, v12
	v_pk_mul_f32 v[6:7], v[6:7], v[16:17]
	v_rcp_f32_e32 v16, v14
	v_rcp_f32_e32 v17, v12
	s_nop 0
	v_pk_mul_f32 v[12:13], v[0:1], v[16:17]
	v_lshlrev_b32_e32 v0, 16, v15
	v_and_b32_e32 v1, 0xffff0000, v15
	v_mul_f32_e32 v14, 0xbfb8aa3b, v0
	v_pk_mul_f32 v[2:3], v[2:3], v[0:1]
	v_mul_f32_e32 v0, 0xbfb8aa3b, v1
	v_exp_f32_e32 v14, v14
	v_exp_f32_e32 v0, v0
	v_cvt_pk_bf16_f32 v1, v6, v7
	v_add_f32_e32 v14, 1.0, v14
	v_add_f32_e32 v0, 1.0, v0
	v_rcp_f32_e32 v14, v14
	v_rcp_f32_e32 v15, v0
	v_cvt_pk_bf16_f32 v0, v4, v5
	v_lshl_add_u64 v[4:5], v[8:9], 0, v[120:121]
	v_pk_mul_f32 v[14:15], v[2:3], v[14:15]
	v_cvt_pk_bf16_f32 v2, v12, v13
	v_cvt_pk_bf16_f32 v3, v14, v15
	global_store_dwordx4 v[4:5], v[0:3], off
	v_lshl_add_u64 v[12:13], v[10:11], 0, v[122:123]
	ds_read_b128 v[4:7], v187 offset:60416
	ds_read_b128 v[0:3], v187 offset:60432
	v_lshl_add_u64 v[10:11], v[10:11], 0, v[126:127]
	s_waitcnt vmcnt(3)
	v_mov_b32_e32 v12, v68
	v_mov_b32_e32 v13, v69
	v_mov_b32_e32 v14, v70
	v_mov_b32_e32 v15, v71
	v_lshlrev_b32_e32 v16, 16, v12
	v_and_b32_e32 v17, 0xffff0000, v12
	v_mul_f32_e32 v12, 0xbfb8aa3b, v16
	v_exp_f32_e32 v12, v12
	s_waitcnt lgkmcnt(1)
	v_pk_mul_f32 v[4:5], v[4:5], v[16:17]
	v_add_f32_e32 v12, 1.0, v12
	v_rcp_f32_e32 v18, v12
	v_mul_f32_e32 v12, 0xbfb8aa3b, v17
	v_exp_f32_e32 v12, v12
	s_nop 0
	v_add_f32_e32 v12, 1.0, v12
	v_rcp_f32_e32 v19, v12
	v_lshlrev_b32_e32 v12, 16, v13
	v_and_b32_e32 v13, 0xffff0000, v13
	v_mul_f32_e32 v16, 0xbfb8aa3b, v12
	v_pk_mul_f32 v[6:7], v[6:7], v[12:13]
	v_mul_f32_e32 v12, 0xbfb8aa3b, v13
	v_exp_f32_e32 v12, v12
	v_exp_f32_e32 v16, v16
	v_and_b32_e32 v13, 0xffff0000, v14
	v_pk_mul_f32 v[4:5], v[4:5], v[18:19]
	v_add_f32_e32 v12, 1.0, v12
	v_rcp_f32_e32 v17, v12
	v_lshlrev_b32_e32 v12, 16, v14
	v_mul_f32_e32 v14, 0xbfb8aa3b, v12
	s_waitcnt lgkmcnt(0)
	v_pk_mul_f32 v[0:1], v[0:1], v[12:13]
	v_mul_f32_e32 v12, 0xbfb8aa3b, v13
	v_add_f32_e32 v16, 1.0, v16
	v_exp_f32_e32 v14, v14
	v_exp_f32_e32 v12, v12
	v_rcp_f32_e32 v16, v16
	v_add_f32_e32 v14, 1.0, v14
	v_add_f32_e32 v12, 1.0, v12
	v_pk_mul_f32 v[6:7], v[6:7], v[16:17]
	v_rcp_f32_e32 v16, v14
	v_rcp_f32_e32 v17, v12
	s_nop 0
	v_pk_mul_f32 v[12:13], v[0:1], v[16:17]
	v_lshlrev_b32_e32 v0, 16, v15
	v_and_b32_e32 v1, 0xffff0000, v15
	v_mul_f32_e32 v14, 0xbfb8aa3b, v0
	v_pk_mul_f32 v[2:3], v[2:3], v[0:1]
	v_mul_f32_e32 v0, 0xbfb8aa3b, v1
	v_exp_f32_e32 v14, v14
	v_exp_f32_e32 v0, v0
	v_cvt_pk_bf16_f32 v1, v6, v7
	v_add_f32_e32 v14, 1.0, v14
	v_add_f32_e32 v0, 1.0, v0
	v_rcp_f32_e32 v14, v14
	v_rcp_f32_e32 v15, v0
	v_cvt_pk_bf16_f32 v0, v4, v5
	v_lshl_add_u64 v[4:5], v[8:9], 0, v[124:125]
	v_pk_mul_f32 v[14:15], v[2:3], v[14:15]
	v_cvt_pk_bf16_f32 v2, v12, v13
	v_cvt_pk_bf16_f32 v3, v14, v15
	global_store_dwordx4 v[4:5], v[0:3], off
	ds_read_b128 v[4:7], v188 offset:60416
	ds_read_b128 v[0:3], v188 offset:60432
	s_waitcnt vmcnt(3)
	v_mov_b32_e32 v10, v72
	v_mov_b32_e32 v11, v73
	v_mov_b32_e32 v12, v74
	v_mov_b32_e32 v13, v75
	v_lshlrev_b32_e32 v14, 16, v10
	v_and_b32_e32 v15, 0xffff0000, v10
	v_mul_f32_e32 v10, 0xbfb8aa3b, v14
	v_exp_f32_e32 v10, v10
	s_waitcnt lgkmcnt(1)
	v_pk_mul_f32 v[4:5], v[4:5], v[14:15]
	v_add_f32_e32 v10, 1.0, v10
	v_rcp_f32_e32 v16, v10
	v_mul_f32_e32 v10, 0xbfb8aa3b, v15
	v_exp_f32_e32 v10, v10
	s_nop 0
	v_add_f32_e32 v10, 1.0, v10
	v_rcp_f32_e32 v17, v10
	v_lshlrev_b32_e32 v10, 16, v11
	v_and_b32_e32 v11, 0xffff0000, v11
	v_mul_f32_e32 v14, 0xbfb8aa3b, v10
	v_pk_mul_f32 v[6:7], v[6:7], v[10:11]
	v_mul_f32_e32 v10, 0xbfb8aa3b, v11
	v_exp_f32_e32 v10, v10
	v_exp_f32_e32 v14, v14
	v_and_b32_e32 v11, 0xffff0000, v12
	v_pk_mul_f32 v[4:5], v[4:5], v[16:17]
	v_add_f32_e32 v10, 1.0, v10
	v_rcp_f32_e32 v15, v10
	v_lshlrev_b32_e32 v10, 16, v12
	v_mul_f32_e32 v12, 0xbfb8aa3b, v10
	s_waitcnt lgkmcnt(0)
	v_pk_mul_f32 v[0:1], v[0:1], v[10:11]
	v_mul_f32_e32 v10, 0xbfb8aa3b, v11
	v_add_f32_e32 v14, 1.0, v14
	v_exp_f32_e32 v12, v12
	v_exp_f32_e32 v10, v10
	v_rcp_f32_e32 v14, v14
	v_add_f32_e32 v12, 1.0, v12
	v_add_f32_e32 v10, 1.0, v10
	v_pk_mul_f32 v[6:7], v[6:7], v[14:15]
	v_rcp_f32_e32 v14, v12
	v_rcp_f32_e32 v15, v10
	s_nop 0
	v_pk_mul_f32 v[10:11], v[0:1], v[14:15]
	v_lshlrev_b32_e32 v0, 16, v13
	v_and_b32_e32 v1, 0xffff0000, v13
	v_mul_f32_e32 v12, 0xbfb8aa3b, v0
	v_pk_mul_f32 v[2:3], v[2:3], v[0:1]
	v_mul_f32_e32 v0, 0xbfb8aa3b, v1
	v_exp_f32_e32 v12, v12
	v_exp_f32_e32 v0, v0
	v_cvt_pk_bf16_f32 v1, v6, v7
	v_add_f32_e32 v12, 1.0, v12
	v_add_f32_e32 v0, 1.0, v0
	v_rcp_f32_e32 v12, v12
	v_rcp_f32_e32 v13, v0
	v_cvt_pk_bf16_f32 v0, v4, v5
	v_lshl_add_u64 v[4:5], v[8:9], 0, v[128:129]
	v_pk_mul_f32 v[12:13], v[2:3], v[12:13]
	v_cvt_pk_bf16_f32 v2, v10, v11
	v_cvt_pk_bf16_f32 v3, v12, v13
	global_store_dwordx4 v[4:5], v[0:3], off
	s_cbranch_scc1 .LBB0_274

.LBB0_381:
	s_or_b64 exec, exec, s[4:5]
	v_add_u32_e32 v8, s26, v120
	ds_read_b128 v[0:3], v8 offset:58112
	ds_read_b128 v[4:7], v8 offset:58144
	s_ashr_i32 s13, s18, 31
	s_add_u32 s4, s29, s18
	s_addc_u32 s5, s30, s13
	s_waitcnt lgkmcnt(1)
	v_mul_f32_e32 v9, v48, v0
	v_mul_f32_e32 v10, v64, v0
	v_mul_f32_e32 v11, v49, v1
	v_mul_f32_e32 v12, v65, v1
	v_mul_f32_e32 v13, v50, v2
	v_mul_f32_e32 v14, v66, v2
	v_mul_f32_e32 v15, v51, v3
	v_mul_f32_e32 v16, v67, v3
	ds_read_b128 v[0:3], v8 offset:58176
	s_lshl_b64 s[4:5], s[4:5], 7
	s_waitcnt lgkmcnt(1)
	v_mul_f32_e32 v17, v52, v4
	v_mul_f32_e32 v4, v68, v4
	v_mul_f32_e32 v18, v53, v5
	s_waitcnt lgkmcnt(0)
	v_mul_f32_e32 v21, v56, v0
	v_mul_f32_e32 v22, v72, v0
	v_mul_f32_e32 v23, v57, v1
	v_mul_f32_e32 v24, v73, v1
	v_mul_f32_e32 v25, v58, v2
	v_mul_f32_e32 v26, v74, v2
	v_mul_f32_e32 v27, v59, v3
	v_mul_f32_e32 v28, v75, v3
	ds_read_b128 v[0:3], v8 offset:58208
	v_mul_f32_e32 v5, v69, v5
	v_mul_f32_e32 v19, v54, v6
	v_mul_f32_e32 v6, v70, v6
	v_mul_f32_e32 v20, v55, v7
	v_mul_f32_e32 v7, v71, v7
	s_waitcnt lgkmcnt(0)
	v_mul_f32_e32 v8, v60, v0
	v_mul_f32_e32 v0, v76, v0
	v_mul_f32_e32 v29, v61, v1
	v_mul_f32_e32 v1, v77, v1
	v_mul_f32_e32 v30, v62, v2
	v_mul_f32_e32 v2, v78, v2
	v_mul_f32_e32 v31, v63, v3
	v_mul_f32_e32 v3, v79, v3
	ds_write_b32 v202, v9 offset:60416
	ds_write_b32 v203, v10 offset:60416
	ds_write_b32 v202, v11 offset:60672
	ds_write_b32 v204, v12 offset:60416
	ds_write_b32 v202, v13 offset:60928
	ds_write_b32 v205, v14 offset:60416
	ds_write_b32 v202, v15 offset:61184
	ds_write_b32 v206, v16 offset:60416
	ds_write_b32 v202, v17 offset:62464
	ds_write_b32 v207, v4 offset:60416
	ds_write_b32 v202, v18 offset:62720
	ds_write_b32 v208, v5 offset:60416
	ds_write_b32 v202, v19 offset:62976
	ds_write_b32 v209, v6 offset:60416
	ds_write_b32 v202, v20 offset:63232
	ds_write_b32 v210, v7 offset:60416
	ds_write_b32 v202, v21 offset:64512
	ds_write_b32 v211, v22 offset:60416
	ds_write_b32 v202, v23 offset:64768
	ds_write_b32 v212, v24 offset:60416
	ds_write_b32 v202, v25 offset:65024
	ds_write_b32 v213, v26 offset:60416
	ds_write_b32 v202, v27 offset:65280
	ds_write_b32 v214, v28 offset:60416
	ds_write_b32 v215, v8
	ds_write_b32 v216, v0 offset:60416
	ds_write_b32 v217, v29
	ds_write_b32 v218, v1 offset:60416
	ds_write_b32 v219, v30
	ds_write_b32 v220, v2 offset:60416
	ds_write_b32 v221, v31
	ds_write_b32 v222, v3 offset:60416
	v_lshl_add_u64 v[10:11], v[124:125], 0, s[4:5]
	v_lshl_add_u64 v[12:13], v[10:11], 0, v[160:161]
	v_lshl_add_u64 v[80:81], v[10:11], 0, v[130:131]
	v_lshl_add_u64 v[84:85], v[10:11], 0, v[134:135]
	v_lshl_add_u64 v[88:89], v[10:11], 0, v[138:139]
	ds_read_b128 v[0:3], v225 offset:60416
	ds_read_b128 v[4:7], v225 offset:60432
	global_load_dwordx4 v[12:15], v[12:13], off
	global_load_dwordx4 v[80:83], v[80:81], off
	global_load_dwordx4 v[84:87], v[84:85], off
	global_load_dwordx4 v[88:91], v[88:89], off
	s_add_u32 s12, s40, s18
	s_addc_u32 s13, s41, s13
	s_lshl_b64 s[12:13], s[12:13], 12
	v_lshl_add_u64 v[8:9], v[146:147], 0, s[12:13]
	s_add_i32 s31, s31, 1
	s_cmp_eq_u32 s31, 4
	s_waitcnt vmcnt(3)
	v_lshlrev_b32_e32 v16, 16, v12
	v_and_b32_e32 v17, 0xffff0000, v12
	v_mul_f32_e32 v12, 0xbfb8aa3b, v16
	v_exp_f32_e32 v12, v12
	s_waitcnt lgkmcnt(1)
	v_pk_mul_f32 v[0:1], v[0:1], v[16:17]
	v_add_f32_e32 v12, 1.0, v12
	v_rcp_f32_e32 v18, v12
	v_mul_f32_e32 v12, 0xbfb8aa3b, v17
	v_exp_f32_e32 v12, v12
	s_nop 0
	v_add_f32_e32 v12, 1.0, v12
	v_rcp_f32_e32 v19, v12
	v_lshlrev_b32_e32 v12, 16, v13
	v_and_b32_e32 v13, 0xffff0000, v13
	v_mul_f32_e32 v16, 0xbfb8aa3b, v12
	v_pk_mul_f32 v[2:3], v[2:3], v[12:13]
	v_mul_f32_e32 v12, 0xbfb8aa3b, v13
	v_exp_f32_e32 v12, v12
	v_exp_f32_e32 v16, v16
	v_and_b32_e32 v13, 0xffff0000, v14
	v_pk_mul_f32 v[0:1], v[0:1], v[18:19]
	v_add_f32_e32 v12, 1.0, v12
	v_rcp_f32_e32 v17, v12
	v_lshlrev_b32_e32 v12, 16, v14
	v_mul_f32_e32 v14, 0xbfb8aa3b, v12
	s_waitcnt lgkmcnt(0)
	v_pk_mul_f32 v[4:5], v[4:5], v[12:13]
	v_mul_f32_e32 v12, 0xbfb8aa3b, v13
	v_add_f32_e32 v16, 1.0, v16
	v_exp_f32_e32 v12, v12
	v_rcp_f32_e32 v16, v16
	v_exp_f32_e32 v14, v14
	v_and_b32_e32 v13, 0xffff0000, v15
	v_add_f32_e32 v12, 1.0, v12
	v_pk_mul_f32 v[2:3], v[2:3], v[16:17]
	v_add_f32_e32 v14, 1.0, v14
	v_rcp_f32_e32 v17, v12
	v_lshlrev_b32_e32 v12, 16, v15
	v_rcp_f32_e32 v16, v14
	v_mul_f32_e32 v14, 0xbfb8aa3b, v12
	v_pk_mul_f32 v[6:7], v[6:7], v[12:13]
	v_mul_f32_e32 v12, 0xbfb8aa3b, v13
	v_exp_f32_e32 v14, v14
	v_exp_f32_e32 v12, v12
	v_pk_mul_f32 v[4:5], v[4:5], v[16:17]
	v_cvt_pk_bf16_f32 v0, v0, v1
	v_add_f32_e32 v14, 1.0, v14
	v_add_f32_e32 v12, 1.0, v12
	v_rcp_f32_e32 v14, v14
	v_rcp_f32_e32 v15, v12
	v_cvt_pk_bf16_f32 v1, v2, v3
	v_cvt_pk_bf16_f32 v2, v4, v5
	v_lshl_add_u64 v[4:5], v[8:9], 0, v[128:129]
	v_pk_mul_f32 v[6:7], v[6:7], v[14:15]
	v_lshl_add_u64 v[12:13], v[10:11], 0, v[130:131]
	v_cvt_pk_bf16_f32 v3, v6, v7
	global_store_dwordx4 v[4:5], v[0:3], off
	ds_read_b128 v[4:7], v226 offset:60416
	ds_read_b128 v[0:3], v226 offset:60432
	s_waitcnt vmcnt(3)
	v_mov_b32_e32 v12, v80
	v_mov_b32_e32 v13, v81
	v_mov_b32_e32 v14, v82
	v_mov_b32_e32 v15, v83
	v_lshlrev_b32_e32 v16, 16, v12
	v_and_b32_e32 v17, 0xffff0000, v12
	v_mul_f32_e32 v12, 0xbfb8aa3b, v16
	v_exp_f32_e32 v12, v12
	s_waitcnt lgkmcnt(1)
	v_pk_mul_f32 v[4:5], v[4:5], v[16:17]
	v_add_f32_e32 v12, 1.0, v12
	v_rcp_f32_e32 v18, v12
	v_mul_f32_e32 v12, 0xbfb8aa3b, v17
	v_exp_f32_e32 v12, v12
	s_nop 0
	v_add_f32_e32 v12, 1.0, v12
	v_rcp_f32_e32 v19, v12
	v_lshlrev_b32_e32 v12, 16, v13
	v_and_b32_e32 v13, 0xffff0000, v13
	v_mul_f32_e32 v16, 0xbfb8aa3b, v12
	v_pk_mul_f32 v[6:7], v[6:7], v[12:13]
	v_mul_f32_e32 v12, 0xbfb8aa3b, v13
	v_exp_f32_e32 v12, v12
	v_exp_f32_e32 v16, v16
	v_and_b32_e32 v13, 0xffff0000, v14
	v_pk_mul_f32 v[4:5], v[4:5], v[18:19]
	v_add_f32_e32 v12, 1.0, v12
	v_rcp_f32_e32 v17, v12
	v_lshlrev_b32_e32 v12, 16, v14
	v_mul_f32_e32 v14, 0xbfb8aa3b, v12
	s_waitcnt lgkmcnt(0)
	v_pk_mul_f32 v[0:1], v[0:1], v[12:13]
	v_mul_f32_e32 v12, 0xbfb8aa3b, v13
	v_add_f32_e32 v16, 1.0, v16
	v_exp_f32_e32 v14, v14
	v_exp_f32_e32 v12, v12
	v_rcp_f32_e32 v16, v16
	v_add_f32_e32 v14, 1.0, v14
	v_add_f32_e32 v12, 1.0, v12
	v_pk_mul_f32 v[6:7], v[6:7], v[16:17]
	v_rcp_f32_e32 v16, v14
	v_rcp_f32_e32 v17, v12
	s_nop 0
	v_pk_mul_f32 v[12:13], v[0:1], v[16:17]
	v_lshlrev_b32_e32 v0, 16, v15
	v_and_b32_e32 v1, 0xffff0000, v15
	v_mul_f32_e32 v14, 0xbfb8aa3b, v0
	v_pk_mul_f32 v[2:3], v[2:3], v[0:1]
	v_mul_f32_e32 v0, 0xbfb8aa3b, v1
	v_exp_f32_e32 v14, v14
	v_exp_f32_e32 v0, v0
	v_cvt_pk_bf16_f32 v1, v6, v7
	v_add_f32_e32 v14, 1.0, v14
	v_add_f32_e32 v0, 1.0, v0
	v_rcp_f32_e32 v14, v14
	v_rcp_f32_e32 v15, v0
	v_cvt_pk_bf16_f32 v0, v4, v5
	v_lshl_add_u64 v[4:5], v[8:9], 0, v[132:133]
	v_pk_mul_f32 v[14:15], v[2:3], v[14:15]
	v_cvt_pk_bf16_f32 v2, v12, v13
	v_cvt_pk_bf16_f32 v3, v14, v15
	global_store_dwordx4 v[4:5], v[0:3], off
	v_lshl_add_u64 v[12:13], v[10:11], 0, v[134:135]
	ds_read_b128 v[4:7], v227 offset:60416
	ds_read_b128 v[0:3], v227 offset:60432
	v_lshl_add_u64 v[10:11], v[10:11], 0, v[138:139]
	s_waitcnt vmcnt(3)
	v_mov_b32_e32 v12, v84
	v_mov_b32_e32 v13, v85
	v_mov_b32_e32 v14, v86
	v_mov_b32_e32 v15, v87
	v_lshlrev_b32_e32 v16, 16, v12
	v_and_b32_e32 v17, 0xffff0000, v12
	v_mul_f32_e32 v12, 0xbfb8aa3b, v16
	v_exp_f32_e32 v12, v12
	s_waitcnt lgkmcnt(1)
	v_pk_mul_f32 v[4:5], v[4:5], v[16:17]
	v_add_f32_e32 v12, 1.0, v12
	v_rcp_f32_e32 v18, v12
	v_mul_f32_e32 v12, 0xbfb8aa3b, v17
	v_exp_f32_e32 v12, v12
	s_nop 0
	v_add_f32_e32 v12, 1.0, v12
	v_rcp_f32_e32 v19, v12
	v_lshlrev_b32_e32 v12, 16, v13
	v_and_b32_e32 v13, 0xffff0000, v13
	v_mul_f32_e32 v16, 0xbfb8aa3b, v12
	v_pk_mul_f32 v[6:7], v[6:7], v[12:13]
	v_mul_f32_e32 v12, 0xbfb8aa3b, v13
	v_exp_f32_e32 v12, v12
	v_exp_f32_e32 v16, v16
	v_and_b32_e32 v13, 0xffff0000, v14
	v_pk_mul_f32 v[4:5], v[4:5], v[18:19]
	v_add_f32_e32 v12, 1.0, v12
	v_rcp_f32_e32 v17, v12
	v_lshlrev_b32_e32 v12, 16, v14
	v_mul_f32_e32 v14, 0xbfb8aa3b, v12
	s_waitcnt lgkmcnt(0)
	v_pk_mul_f32 v[0:1], v[0:1], v[12:13]
	v_mul_f32_e32 v12, 0xbfb8aa3b, v13
	v_add_f32_e32 v16, 1.0, v16
	v_exp_f32_e32 v14, v14
	v_exp_f32_e32 v12, v12
	v_rcp_f32_e32 v16, v16
	v_add_f32_e32 v14, 1.0, v14
	v_add_f32_e32 v12, 1.0, v12
	v_pk_mul_f32 v[6:7], v[6:7], v[16:17]
	v_rcp_f32_e32 v16, v14
	v_rcp_f32_e32 v17, v12
	s_nop 0
	v_pk_mul_f32 v[12:13], v[0:1], v[16:17]
	v_lshlrev_b32_e32 v0, 16, v15
	v_and_b32_e32 v1, 0xffff0000, v15
	v_mul_f32_e32 v14, 0xbfb8aa3b, v0
	v_pk_mul_f32 v[2:3], v[2:3], v[0:1]
	v_mul_f32_e32 v0, 0xbfb8aa3b, v1
	v_exp_f32_e32 v14, v14
	v_exp_f32_e32 v0, v0
	v_cvt_pk_bf16_f32 v1, v6, v7
	v_add_f32_e32 v14, 1.0, v14
	v_add_f32_e32 v0, 1.0, v0
	v_rcp_f32_e32 v14, v14
	v_rcp_f32_e32 v15, v0
	v_cvt_pk_bf16_f32 v0, v4, v5
	v_lshl_add_u64 v[4:5], v[8:9], 0, v[136:137]
	v_pk_mul_f32 v[14:15], v[2:3], v[14:15]
	v_cvt_pk_bf16_f32 v2, v12, v13
	v_cvt_pk_bf16_f32 v3, v14, v15
	global_store_dwordx4 v[4:5], v[0:3], off
	ds_read_b128 v[4:7], v228 offset:60416
	ds_read_b128 v[0:3], v228 offset:60432
	s_waitcnt vmcnt(3)
	v_mov_b32_e32 v10, v88
	v_mov_b32_e32 v11, v89
	v_mov_b32_e32 v12, v90
	v_mov_b32_e32 v13, v91
	v_lshlrev_b32_e32 v14, 16, v10
	v_and_b32_e32 v15, 0xffff0000, v10
	v_mul_f32_e32 v10, 0xbfb8aa3b, v14
	v_exp_f32_e32 v10, v10
	s_waitcnt lgkmcnt(1)
	v_pk_mul_f32 v[4:5], v[4:5], v[14:15]
	v_add_f32_e32 v10, 1.0, v10
	v_rcp_f32_e32 v16, v10
	v_mul_f32_e32 v10, 0xbfb8aa3b, v15
	v_exp_f32_e32 v10, v10
	s_nop 0
	v_add_f32_e32 v10, 1.0, v10
	v_rcp_f32_e32 v17, v10
	v_lshlrev_b32_e32 v10, 16, v11
	v_and_b32_e32 v11, 0xffff0000, v11
	v_mul_f32_e32 v14, 0xbfb8aa3b, v10
	v_pk_mul_f32 v[6:7], v[6:7], v[10:11]
	v_mul_f32_e32 v10, 0xbfb8aa3b, v11
	v_exp_f32_e32 v10, v10
	v_exp_f32_e32 v14, v14
	v_and_b32_e32 v11, 0xffff0000, v12
	v_pk_mul_f32 v[4:5], v[4:5], v[16:17]
	v_add_f32_e32 v10, 1.0, v10
	v_rcp_f32_e32 v15, v10
	v_lshlrev_b32_e32 v10, 16, v12
	v_mul_f32_e32 v12, 0xbfb8aa3b, v10
	s_waitcnt lgkmcnt(0)
	v_pk_mul_f32 v[0:1], v[0:1], v[10:11]
	v_mul_f32_e32 v10, 0xbfb8aa3b, v11
	v_add_f32_e32 v14, 1.0, v14
	v_exp_f32_e32 v12, v12
	v_exp_f32_e32 v10, v10
	v_rcp_f32_e32 v14, v14
	v_add_f32_e32 v12, 1.0, v12
	v_add_f32_e32 v10, 1.0, v10
	v_pk_mul_f32 v[6:7], v[6:7], v[14:15]
	v_rcp_f32_e32 v14, v12
	v_rcp_f32_e32 v15, v10
	s_nop 0
	v_pk_mul_f32 v[10:11], v[0:1], v[14:15]
	v_lshlrev_b32_e32 v0, 16, v13
	v_and_b32_e32 v1, 0xffff0000, v13
	v_mul_f32_e32 v12, 0xbfb8aa3b, v0
	v_pk_mul_f32 v[2:3], v[2:3], v[0:1]
	v_mul_f32_e32 v0, 0xbfb8aa3b, v1
	v_exp_f32_e32 v12, v12
	v_exp_f32_e32 v0, v0
	v_cvt_pk_bf16_f32 v1, v6, v7
	v_add_f32_e32 v12, 1.0, v12
	v_add_f32_e32 v0, 1.0, v0
	v_rcp_f32_e32 v12, v12
	v_rcp_f32_e32 v13, v0
	v_cvt_pk_bf16_f32 v0, v4, v5
	v_lshl_add_u64 v[4:5], v[8:9], 0, v[140:141]
	v_pk_mul_f32 v[12:13], v[2:3], v[12:13]
	v_cvt_pk_bf16_f32 v2, v10, v11
	v_cvt_pk_bf16_f32 v3, v12, v13
	global_store_dwordx4 v[4:5], v[0:3], off
	s_cbranch_scc1 .LBB0_379
